# sample_ml: 12 of 16 state loads hoisted above the q/k/v, gate and n0 load waits of each job (counted waits adjusted)
# speedup vs baseline: 1.0168x; 1.0016x over previous
; __device__ __forceinline__ float bf_lo(unsigned u) { return __uint_as_float(u << 16); }
; __device__ __forceinline__ float bf_hi(unsigned u) { return __uint_as_float(u & 0xffff0000u); }
; __device__ __forceinline__ float logsig_f(float x) { return fminf(x, 0.f) - log1pf(__expf(-fabsf(x))); }
; __device__ __forceinline__ void sample_ml(const Params& p, unsigned char* smem, int job) {
;     ...
;     {
;         const int t = tid >> 6, c = tid & 63;
;         const size_t r = (size_t)(rowb + t) * N1P;
;         const unsigned qq = *(const unsigned*)(U + r + UC_Q + h * 128 + 2 * c), kk = *(const unsigned*)(U + r + UC_K + h * 128 + 2 * c);
;         const u32x2 vv = *(const u32x2*)(U + r + UC_V + h * 256 + 4 * c);
;         qs[t * 128 + 2 * c] = bf_lo(qq); qs[t * 128 + 2 * c + 1] = bf_hi(qq);
;         ks[t * 128 + 2 * c] = bf_lo(kk) * 0.08838834764831845f; ks[t * 128 + 2 * c + 1] = bf_hi(kk) * 0.08838834764831845f;
;         *(f32x4*)(vs + t * 256 + 4 * c) = (f32x4){bf_lo(vv[0]), bf_hi(vv[0]), bf_lo(vv[1]), bf_hi(vv[1])};
;         if (tid < 8) { sig[tid] = SF[(size_t)(rowb + tid) * 64 + 32 + h] + p.in[17][h]; slf[tid] = logsig_f(SF[(size_t)(rowb + tid) * 64 + 40 + h] + p.in[18][h]); }
;         if (tid >= 128 && tid < 256) n0v[tid - 128] = p.in[5][(size_t)(b * 8 + h) * 128 + tid - 128];
;     }
;     const int v4 = lane, dg = wid;
;     const size_t coff = ((size_t)(b * 8 + h) * 128 + dg * 16) * 256 + v4 * 4;
;     f32x4 c0[16];
; #pragma unroll
;     for (int i = 0; i < 16; ++i) c0[i] = __builtin_nontemporal_load((const f32x4*)(p.in[4] + coff + (size_t)i * 256));
.LBB0_715:
	v_mov_b32_e32 v116, v151
	s_and_b32 s0, s2, -8
	s_add_i32 s29, s0, 0x2000
	s_waitcnt vmcnt(0)
	v_ashrrev_i32_e32 v10, 6, v116
	s_and_b32 s28, s2, 7
	v_add_u32_e32 v6, s29, v10
	s_waitcnt lgkmcnt(0)
	v_mov_b64_e32 v[4:5], s[18:19]
	v_and_b32_e32 v132, 63, v116
	v_mad_i64_i32 v[4:5], s[4:5], v6, s45, v[4:5]
	s_lshl_b32 s96, s28, 8
	v_lshl_add_u64 v[6:7], v[4:5], 0, s[96:97]
	v_lshlrev_b32_e32 v148, 2, v132
	v_lshl_add_u64 v[6:7], v[6:7], 0, v[148:149]
	s_movk_i32 s1, 0x2000
	v_add_co_u32_e32 v6, vcc, s1, v6
	s_lshl_b32 s4, s28, 9
	s_nop 0
	v_addc_co_u32_e32 v7, vcc, 0, v7, vcc
	s_mov_b32 s5, s97
	global_load_dword v11, v[6:7], off offset:1088
	global_load_dword v13, v[6:7], off offset:3136
	v_lshl_add_u64 v[4:5], v[4:5], 0, s[4:5]
	v_lshlrev_b32_e32 v6, 3, v132
	v_mov_b32_e32 v7, v149
	v_lshl_add_u64 v[4:5], v[4:5], 0, v[6:7]
	s_movk_i32 s1, 0x3000
	v_add_co_u32_e32 v4, vcc, s1, v4
	v_lshl_or_b32 v6, v10, 9, v6
	s_nop 0
	v_addc_co_u32_e32 v5, vcc, 0, v5, vcc
	global_load_dwordx2 v[8:9], v[4:5], off offset:1088
	v_readfirstlane_b32 s1, v10
	s_ashr_i32 s3, s2, 31
	s_lshl_b32 s1, s1, 4
	s_lshl_b64 s[4:5], s[2:3], 7
	s_add_u32 s6, s4, s1
	s_addc_u32 s7, s5, 0
	s_lshl_b64 s[6:7], s[6:7], 8
	v_readlane_b32 s4, v254, 51
	v_readlane_b32 s5, v254, 52
	v_mov_b32_e32 v215, s7
	v_or_b32_e32 v214, s6, v148
	s_movk_i32 s6, 0x2000
	s_mov_b32 s7, 0
	v_lshl_add_u64 v[214:215], v[214:215], 2, s[4:5]
	v_lshl_add_u64 v[216:217], v[214:215], 0, s[6:7]
	global_load_dwordx4 v[96:99], v[214:215], off nt
	global_load_dwordx4 v[92:95], v[214:215], off offset:1024 nt
	global_load_dwordx4 v[88:91], v[214:215], off offset:2048 nt
	global_load_dwordx4 v[84:87], v[214:215], off offset:3072 nt
	global_load_dwordx4 v[76:79], v[216:217], off offset:-3072 nt
	global_load_dwordx4 v[72:75], v[216:217], off offset:-2048 nt
	global_load_dwordx4 v[80:83], v[216:217], off offset:-4096 nt
	global_load_dwordx4 v[64:67], v[216:217], off nt
	global_load_dwordx4 v[60:63], v[216:217], off offset:1024 nt
	global_load_dwordx4 v[56:59], v[216:217], off offset:2048 nt
	global_load_dwordx4 v[52:55], v[216:217], off offset:3072 nt
	global_load_dwordx4 v[68:71], v[216:217], off offset:-1024 nt
	v_lshlrev_b32_e32 v4, 10, v10
	v_lshlrev_b32_e32 v5, 4, v132
	v_cmp_gt_i32_e32 vcc, 8, v116
	v_readfirstlane_b32 s30, v10
	v_add3_u32 v14, 0, v4, v5
	v_add_u32_e32 v15, 0, v6
	v_lshl_add_u32 v133, v116, 2, 0
	s_waitcnt vmcnt(14)
	v_lshlrev_b32_e32 v10, 16, v11
	s_waitcnt vmcnt(13)
	v_lshlrev_b32_e32 v12, 16, v13
	v_and_b32_e32 v13, 0xffff0000, v13
	v_and_b32_e32 v11, 0xffff0000, v11
	s_waitcnt vmcnt(12)
	v_lshlrev_b32_e32 v4, 16, v8
	v_and_b32_e32 v5, 0xffff0000, v8
	v_lshlrev_b32_e32 v6, 16, v9
	v_and_b32_e32 v7, 0xffff0000, v9
	v_pk_mul_f32 v[8:9], v[12:13], s[90:91] op_sel_hi:[1,0]
	ds_write2st64_b64 v15, v[10:11], v[8:9] offset1:8
	ds_write_b128 v14, v[4:7] offset:8192
	s_and_saveexec_b64 s[4:5], vcc
	s_cbranch_execz .LBB0_717
; __device__ __forceinline__ float logsig_f(float x) { return fminf(x, 0.f) - log1pf(__expf(-fabsf(x))); }
; __device__ __forceinline__ void sample_ml(const Params& p, unsigned char* smem, int job) {
;     ...
;         if (tid < 8) { sig[tid] = SF[(size_t)(rowb + tid) * 64 + 32 + h] + p.in[17][h]; slf[tid] = logsig_f(SF[(size_t)(rowb + tid) * 64 + 40 + h] + p.in[18][h]); }
	v_add_u32_e32 v4, s29, v116
	v_ashrrev_i32_e32 v5, 31, v4
	v_lshlrev_b64 v[4:5], 8, v[4:5]
	v_lshl_add_u64 v[4:5], s[20:21], 0, v[4:5]
	s_lshl_b32 s6, s28, 2
	s_mov_b32 s7, s97
	v_readlane_b32 s56, v255, 11
	v_lshl_add_u64 v[6:7], v[4:5], 0, s[6:7]
	v_mov_b32_e32 v5, s6
	v_readlane_b32 s58, v255, 13
	v_readlane_b32 s59, v255, 14
	global_load_dword v4, v[6:7], off offset:128
	v_readlane_b32 s60, v255, 15
	v_readlane_b32 s61, v255, 16
	s_mov_b32 s1, 0xbfb8aa3b
	s_mov_b32 s6, 0x3f317218
	global_load_dword v8, v5, s[58:59]
	s_nop 0
	global_load_dword v6, v[6:7], off offset:160
	s_nop 0
	global_load_dword v5, v5, s[60:61]
	v_readlane_b32 s57, v255, 12
	v_readlane_b32 s62, v255, 17
	v_readlane_b32 s63, v255, 18
	v_readlane_b32 s64, v255, 19
	v_readlane_b32 s65, v255, 20
	v_readlane_b32 s66, v255, 21
	v_readlane_b32 s67, v255, 22
	v_readlane_b32 s68, v255, 23
	v_readlane_b32 s69, v255, 24
	v_readlane_b32 s70, v255, 25
	v_readlane_b32 s71, v255, 26
	s_waitcnt vmcnt(2)
	v_add_f32_e32 v4, v4, v8
	s_waitcnt vmcnt(0)
	v_add_f32_e32 v6, v6, v5
	v_min_f32_e32 v5, 0, v6
	v_mul_f32_e64 v6, |v6|, s1
	v_exp_f32_e32 v6, v6
	s_mov_b32 s1, 0x3f2aaaab
	v_add_f32_e32 v7, 1.0, v6
	v_add_f32_e32 v8, -1.0, v7
	v_sub_f32_e32 v9, v8, v7
	v_add_f32_e32 v9, 1.0, v9
	v_sub_f32_e32 v8, v6, v8
	v_add_f32_e32 v10, v8, v9
	v_frexp_mant_f32_e32 v8, v7
	v_cmp_gt_f32_e32 vcc, s1, v8
	v_cvt_f64_f32_e32 v[8:9], v7
	v_frexp_exp_i32_f64_e32 v8, v[8:9]
	v_subbrev_co_u32_e32 v8, vcc, 0, v8, vcc
	v_sub_u32_e32 v9, 0, v8
	v_ldexp_f32 v7, v7, v9
	v_ldexp_f32 v9, v10, v9
	v_add_f32_e32 v10, -1.0, v7
	v_add_f32_e32 v11, 1.0, v10
	v_sub_f32_e32 v11, v7, v11
	v_add_f32_e32 v11, v9, v11
	v_add_f32_e32 v12, v10, v11
	v_sub_f32_e32 v10, v12, v10
	v_sub_f32_e32 v10, v11, v10
	v_add_f32_e32 v11, 1.0, v7
	v_add_f32_e32 v13, -1.0, v11
	v_sub_f32_e32 v7, v7, v13
	v_add_f32_e32 v7, v9, v7
	v_add_f32_e32 v9, v11, v7
	v_sub_f32_e32 v11, v9, v11
	v_sub_f32_e32 v7, v7, v11
	v_rcp_f32_e32 v11, v9
	v_cvt_f32_i32_e32 v8, v8
	s_mov_b32 s1, 0x7f800000
	v_cmp_neq_f32_e32 vcc, s1, v6
	v_mul_f32_e32 v13, v12, v11
	v_mul_f32_e32 v14, v9, v13
	v_fma_f32 v15, v13, v9, -v14
	v_fmac_f32_e32 v15, v13, v7
	v_add_f32_e32 v16, v14, v15
	v_sub_f32_e32 v17, v12, v16
	v_sub_f32_e32 v12, v12, v17
	v_sub_f32_e32 v14, v16, v14
	v_sub_f32_e32 v12, v12, v16
	v_add_f32_e32 v10, v10, v12
	v_sub_f32_e32 v12, v14, v15
	v_add_f32_e32 v10, v12, v10
	v_add_f32_e32 v12, v17, v10
	v_mul_f32_e32 v14, v11, v12
	v_mul_f32_e32 v15, v9, v14
	v_fma_f32 v9, v14, v9, -v15
	v_fmac_f32_e32 v9, v14, v7
	v_sub_f32_e32 v7, v17, v12
	v_add_f32_e32 v7, v10, v7
	v_add_f32_e32 v10, v15, v9
	v_sub_f32_e32 v16, v12, v10
	v_sub_f32_e32 v12, v12, v16
	v_sub_f32_e32 v15, v10, v15
	v_sub_f32_e32 v10, v12, v10
	v_add_f32_e32 v7, v7, v10
	v_sub_f32_e32 v9, v15, v9
	v_add_f32_e32 v7, v9, v7
	v_add_f32_e32 v9, v13, v14
	v_add_f32_e32 v7, v16, v7
	v_sub_f32_e32 v10, v9, v13
	v_mul_f32_e32 v7, v11, v7
	v_sub_f32_e32 v10, v14, v10
	v_add_f32_e32 v7, v10, v7
	v_mul_f32_e32 v13, 0x3f317218, v8
	v_add_f32_e32 v10, v9, v7
	v_fma_f32 v14, v8, s6, -v13
	v_mul_f32_e32 v11, v10, v10
	v_fmac_f32_e32 v14, 0xb102e308, v8
	v_sub_f32_e32 v8, v10, v9
	v_fmamk_f32 v12, v11, 0x3e9b6dac, v150
	v_sub_f32_e32 v7, v7, v8
	v_add_f32_e32 v8, v13, v14
	v_fmaak_f32 v12, v11, v12, 0x3f2aaada
	v_sub_f32_e32 v9, v8, v13
	v_ldexp_f32 v13, v10, 1
	v_mul_f32_e32 v10, v10, v11
	v_mul_f32_e32 v10, v10, v12
	v_add_f32_e32 v11, v13, v10
	v_sub_f32_e32 v12, v11, v13
	v_ldexp_f32 v7, v7, 1
	v_sub_f32_e32 v10, v10, v12
	v_add_f32_e32 v7, v7, v10
	v_add_f32_e32 v10, v11, v7
	v_sub_f32_e32 v11, v10, v11
	v_sub_f32_e32 v7, v7, v11
	v_add_f32_e32 v11, v8, v10
	v_sub_f32_e32 v12, v11, v8
	v_sub_f32_e32 v13, v11, v12
	v_sub_f32_e32 v9, v14, v9
	v_sub_f32_e32 v8, v8, v13
	v_sub_f32_e32 v10, v10, v12
	v_add_f32_e32 v8, v10, v8
	v_add_f32_e32 v10, v9, v7
	v_sub_f32_e32 v12, v10, v9
	v_sub_f32_e32 v13, v10, v12
	v_sub_f32_e32 v9, v9, v13
	v_sub_f32_e32 v7, v7, v12
	v_add_f32_e32 v8, v10, v8
	v_add_f32_e32 v7, v7, v9
	v_add_f32_e32 v9, v11, v8
	v_sub_f32_e32 v10, v9, v11
	v_sub_f32_e32 v8, v8, v10
	v_add_f32_e32 v7, v7, v8
	v_add_f32_e32 v7, v9, v7
	v_cndmask_b32_e32 v7, v210, v7, vcc
	v_cmp_ngt_f32_e32 vcc, -1.0, v6
	s_mov_b32 s1, 0x33800000
	s_nop 0
	v_cndmask_b32_e32 v7, v211, v7, vcc
	v_cmp_neq_f32_e32 vcc, -1.0, v6
	s_nop 1
	v_cndmask_b32_e32 v7, v212, v7, vcc
	v_cmp_lt_f32_e64 vcc, |v6|, s1
	s_nop 1
	v_cndmask_b32_e32 v6, v7, v6, vcc
	v_sub_f32_e32 v5, v5, v6
	v_add_u32_e32 v6, 0x4000, v133
	ds_write2_b32 v6, v4, v5 offset0:64 offset1:72

; __device__ __forceinline__ void sample_ml(const Params& p, unsigned char* smem, int job) {
;     ...
;     for (int i = 0; i < 16; ++i) c0[i] = __builtin_nontemporal_load((const f32x4*)(p.in[4] + coff + (size_t)i * 256));
;     const float mp = p.in[6][b * 8 + h];
;     __syncthreads();
;     float F[8], gg[8], M[8];
;     { float run = 0.f, pm = -INFINITY;
; #pragma unroll
;       for (int t = 0; t < 8; ++t) { run += slf[t]; F[t] = run; gg[t] = sig[t] - run; pm = fmaxf(pm, gg[t]); M[t] = fmaxf(pm, mp); } }
;     const float Ml = M[7], dec = __expf(mp - Ml), m_new = F[7] + Ml;
;     {
;         const int pair = tid >> 3, part = tid & 7, t = pair >> 3, s = pair & 7;
;         float sum = 0.f;
; #pragma unroll
;         for (int i = 0; i < 4; ++i) {
;             const f32x4 a4 = *(const f32x4*)(qs + t * 128 + part * 16 + i * 4), b4 = *(const f32x4*)(ks + s * 128 + part * 16 + i * 4);
;             sum += a4[0] * b4[0] + a4[1] * b4[1] + a4[2] * b4[2] + a4[3] * b4[3];
;         }
;         sum += __shfl_xor(sum, 1); sum += __shfl_xor(sum, 2); sum += __shfl_xor(sum, 4);
;         if (part == 0) QK[pair] = sum;
.LBB0_719:
	s_or_b64 exec, exec, s[4:5]
	s_lshl_b32 s1, s30, 4
	s_lshl_b64 s[4:5], s[2:3], 7
	s_ashr_i32 s7, s1, 31
	s_add_u32 s6, s4, s1
	s_addc_u32 s7, s5, s7
	s_lshl_b64 s[6:7], s[6:7], 8
	v_readlane_b32 s56, v254, 43
	v_mov_b32_e32 v101, s7
	v_or_b32_e32 v100, s6, v148
	v_readlane_b32 s64, v254, 51
	v_readlane_b32 s65, v254, 52
	s_movk_i32 s6, 0x1000
	v_readlane_b32 s68, v254, 55
	v_lshl_add_u64 v[4:5], v[100:101], 2, s[64:65]
	v_add_co_u32_e32 v6, vcc, s6, v4
	s_movk_i32 s6, 0x2000
	s_nop 0
	v_addc_co_u32_e32 v7, vcc, 0, v5, vcc
	v_add_co_u32_e32 v8, vcc, s6, v4
	s_movk_i32 s6, 0x3000
	s_nop 0
	v_addc_co_u32_e32 v9, vcc, 0, v5, vcc
	v_add_co_u32_e32 v4, vcc, s6, v4
	s_lshl_b64 s[6:7], s[2:3], 2
	s_nop 0
	v_addc_co_u32_e32 v5, vcc, 0, v5, vcc
	global_load_dwordx4 v[48:51], v[4:5], off nt
	global_load_dwordx4 v[12:15], v[4:5], off offset:1024 nt
	global_load_dwordx4 v[8:11], v[4:5], off offset:2048 nt
	s_nop 0
	global_load_dwordx4 v[4:7], v[4:5], off offset:3072 nt
	v_readlane_b32 s69, v254, 56
	s_add_u32 s6, s68, s6
	s_addc_u32 s7, s69, s7
	global_load_dword v171, v149, s[6:7]
	v_and_b32_e32 v46, 7, v116
	v_lshlrev_b32_e32 v16, 3, v116
	v_ashrrev_i32_e32 v32, 3, v116
	v_and_b32_e32 v16, 0xfffffe00, v16
	v_lshlrev_b32_e32 v17, 6, v46
	v_add3_u32 v33, 0, v16, v17
	v_lshlrev_b32_e32 v16, 9, v32
	v_and_b32_e32 v16, 0xe00, v16
	s_waitcnt lgkmcnt(0)
	s_barrier
	v_add3_u32 v47, 0, v16, v17
	ds_read_b128 v[16:19], v33
	ds_read_b128 v[20:23], v33 offset:16
	ds_read_b128 v[24:27], v47 offset:4096
	ds_read_b128 v[28:31], v33 offset:32
	ds_read_b128 v[34:37], v33 offset:48
	ds_read_b128 v[38:41], v47 offset:4112
	ds_read_b128 v[42:45], v47 offset:4128
	ds_read_b128 v[102:105], v47 offset:4144
	s_waitcnt lgkmcnt(5)
	v_mul_f32_e32 v17, v17, v25
	v_fmac_f32_e32 v17, v16, v24
	v_fmac_f32_e32 v17, v18, v26
	v_fmac_f32_e32 v17, v19, v27
	v_add_f32_e32 v16, 0, v17
	s_waitcnt lgkmcnt(2)
	v_mul_f32_e32 v17, v21, v39
	v_fmac_f32_e32 v17, v20, v38
	v_fmac_f32_e32 v17, v22, v40
	v_fmac_f32_e32 v17, v23, v41
	v_add_f32_e32 v16, v16, v17
	s_waitcnt lgkmcnt(1)
	v_mul_f32_e32 v17, v29, v43
	v_fmac_f32_e32 v17, v28, v42
	v_fmac_f32_e32 v17, v30, v44
	v_fmac_f32_e32 v17, v31, v45
	v_add_f32_e32 v16, v16, v17
	s_waitcnt lgkmcnt(0)
	v_mul_f32_e32 v17, v35, v103
	v_fmac_f32_e32 v17, v34, v102
	v_fmac_f32_e32 v17, v36, v104
	v_fmac_f32_e32 v17, v37, v105
	v_and_b32_e32 v18, 64, v206
	v_add_f32_e32 v16, v16, v17
	v_xor_b32_e32 v17, 1, v206
	v_add_u32_e32 v33, 64, v18
	v_cmp_lt_i32_e32 vcc, v17, v33
	v_readlane_b32 s57, v254, 44
	v_readlane_b32 s58, v254, 45
	v_cndmask_b32_e32 v17, v206, v17, vcc
	v_lshlrev_b32_e32 v134, 2, v17
	ds_bpermute_b32 v17, v134, v16
	v_readlane_b32 s59, v254, 46
	v_readlane_b32 s60, v254, 47
	v_readlane_b32 s61, v254, 48
	v_readlane_b32 s62, v254, 49
	s_waitcnt lgkmcnt(0)
	v_add_f32_e32 v34, v16, v17
	v_xor_b32_e32 v16, 2, v206
	v_cmp_lt_i32_e32 vcc, v16, v33
	v_readlane_b32 s63, v254, 50
	v_readlane_b32 s66, v254, 53
	v_cndmask_b32_e32 v16, v206, v16, vcc
	v_lshlrev_b32_e32 v135, 2, v16
	ds_bpermute_b32 v35, v135, v34
	ds_read_b128 v[24:27], v149 offset:16640
	ds_read_b128 v[16:19], v149 offset:16656
	ds_read_b128 v[28:31], v149 offset:16672
	ds_read_b128 v[20:23], v149 offset:16688
	v_readlane_b32 s67, v254, 54
	v_readlane_b32 s70, v254, 57
	v_readlane_b32 s71, v254, 58
	s_waitcnt lgkmcnt(4)
	v_add_f32_e32 v34, v34, v35
	v_xor_b32_e32 v35, 4, v206
	v_cmp_lt_i32_e32 vcc, v35, v33
	s_nop 1
	v_cndmask_b32_e32 v35, v206, v35, vcc
	v_lshlrev_b32_e32 v136, 2, v35
	ds_bpermute_b32 v35, v136, v34
	v_cmp_eq_u32_e32 vcc, 0, v46
	s_and_saveexec_b64 s[6:7], vcc
	s_cbranch_execz .LBB0_721
	v_lshl_add_u32 v32, v32, 2, 0
	s_waitcnt lgkmcnt(0)
	v_add_f32_e32 v34, v34, v35
	ds_write_b32 v32, v34 offset:16384
